# attention Q rows fetched as whole 128-byte lines by lane pairs (DPP un-shuffle), non-temporal
# baseline (speedup 1.0000x reference)
.LBB0_174:
	v_writelane_b32 v248, s10, 5
	v_writelane_b32 v248, s16, 3
	s_nop 1
	v_writelane_b32 v248, s17, 4
	s_or_b64 exec, exec, s[4:5]
	v_readlane_b32 s4, v249, 15
	v_readlane_b32 s5, v249, 16
	s_andn2_b64 vcc, exec, s[4:5]
	s_cbranch_vccnz .LBB0_203
	s_waitcnt lgkmcnt(0)
	s_barrier
	v_readfirstlane_b32 s67, v158
	s_lshr_b32 s67, s67, 6
	s_lshr_b32 s68, s67, 2
	v_and_b32_e32 v0, 63, v158
	v_and_b32_e32 v1, 15, v0
	v_lshrrev_b32_e32 v2, 4, v0
	s_lshl_b32 s4, s67, 4
	v_add_u32_e32 v17, s4, v1
	v_and_b32_e32 v37, 6, v1
	v_xor_b32_e32 v37, v2, v37
	v_lshlrev_b32_e32 v37, 4, v37
	v_lshl_add_u32 v4, v1, 7, v37
	v_xor_b32_e32 v5, 64, v4
	v_lshrrev_b32_e32 v38, 2, v1
	v_lshl_add_u32 v38, v2, 2, v38
	v_add_u32_e32 v39, s4, v38
	v_and_b32_e32 v40, 6, v38
	v_and_b32_e32 v41, 3, v1
	v_lshrrev_b32_e32 v42, 1, v41
	v_and_b32_e32 v43, 1, v1
	v_lshlrev_b32_e32 v43, 3, v43
	v_add_u32_e32 v45, 0x90, v39
	v_and_b32_e32 v45, 0xff, v45
	v_or_b32_e32 v44, 0, v42
	v_xor_b32_e32 v44, v44, v40
	v_lshlrev_b32_e32 v44, 4, v44
	v_add_u32_e32 v44, v44, v43
	v_lshl_add_u32 v46, v38, 7, v44
	v_add_u32_e32 v6, 0x10000, v46
	v_or_b32_e32 v44, 2, v42
	v_xor_b32_e32 v44, v44, v40
	v_lshlrev_b32_e32 v44, 4, v44
	v_add_u32_e32 v44, v44, v43
	v_lshl_add_u32 v46, v38, 7, v44
	v_add_u32_e32 v7, 0x10000, v46
	v_or_b32_e32 v44, 4, v42
	v_xor_b32_e32 v44, v44, v40
	v_lshlrev_b32_e32 v44, 4, v44
	v_add_u32_e32 v44, v44, v43
	v_lshl_add_u32 v46, v38, 7, v44
	v_add_u32_e32 v8, 0x10000, v46
	v_or_b32_e32 v44, 6, v42
	v_xor_b32_e32 v44, v44, v40
	v_lshlrev_b32_e32 v44, 4, v44
	v_add_u32_e32 v44, v44, v43
	v_lshl_add_u32 v46, v38, 7, v44
	v_add_u32_e32 v9, 0x10000, v46
	v_lshrrev_b32_e32 v14, 3, v158
	v_and_b32_e32 v44, 7, v0
	v_lshrrev_b32_e32 v45, 3, v0
	v_and_b32_e32 v45, 6, v45
	v_xor_b32_e32 v44, v44, v45
	v_lshlrev_b32_e32 v15, 4, v44
	v_lshlrev_b32_e32 v44, 2, v2
	v_sub_u32_e32 v45, v1, v44
	v_add_u32_e32 v45, 0x80, v45
	v_cvt_f32_i32_e32 v16, v45
	v_and_b32_e32 v46, 1, v1
	v_lshlrev_b32_e32 v46, 6, v46
	v_lshl_or_b32 v18, v2, 4, v46
	v_and_b32_e32 v156, -2, v17
	v_or_b32_e32 v157, 1, v17
	s_mov_b32 s94, 0xaaaaaaaa
	s_mov_b32 s95, 0xaaaaaaaa
	v_and_b32_e32 v46, 1, v2
	v_lshlrev_b32_e32 v46, 5, v46
	v_lshrrev_b32_e32 v47, 1, v2
	v_lshl_or_b32 v19, v47, 4, v46
	v_or_b32_e32 v45, 0, v44
	v_cmp_lt_u32_e64 s[54:55], v45, v1
	v_cmp_gt_u32_e64 s[70:71], v45, v1
	v_or_b32_e32 v45, 1, v44
	v_cmp_lt_u32_e64 s[56:57], v45, v1
	v_cmp_gt_u32_e64 s[72:73], v45, v1
	v_or_b32_e32 v45, 2, v44
	v_cmp_lt_u32_e64 s[58:59], v45, v1
	v_cmp_gt_u32_e64 s[74:75], v45, v1
	v_or_b32_e32 v45, 3, v44
	v_cmp_lt_u32_e64 s[60:61], v45, v1
	v_cmp_gt_u32_e64 s[76:77], v45, v1
	v_mov_b32_e32 v190, 0
	v_mov_b32_e32 v191, 0
	s_mov_b32 s63, s2

.Latt_half_3:
	s_add_i32 s7, s5, 128
	s_and_b32 s7, s7, 511
	s_lshl_b32 s7, s7, 7
	s_add_i32 m0, s7, s9
	s_add_i32 s7, s6, 128
	v_add_u32_e32 v0, s7, v14
	v_lshlrev_b32_e32 v0, s28, v0
	v_add_u32_e32 v0, s29, v0
	v_max_i32_e32 v0, 0, v0
	v_lshl_or_b32 v2, v0, 7, v15
	v_lshl_add_u64 v[42:43], s[38:39], 0, v[2:3]
	global_load_lds_dwordx4 v[42:43], off nt
	s_add_i32 s7, s5, 192
	s_and_b32 s7, s7, 511
	s_lshl_b32 s7, s7, 7
	s_add_i32 m0, s7, s9
	s_add_i32 s7, s6, 192
	v_add_u32_e32 v0, s7, v14
	v_lshlrev_b32_e32 v0, s28, v0
	v_add_u32_e32 v0, s29, v0
	v_max_i32_e32 v0, 0, v0
	v_lshl_or_b32 v2, v0, 7, v15
	v_lshl_add_u64 v[44:45], s[38:39], 0, v[2:3]
	global_load_lds_dwordx4 v[44:45], off nt
	s_lshl_b32 s5, s30, 7
	v_add_u32_e32 v82, s5, v17
	v_lshlrev_b32_e32 v82, s28, v82
	v_add_u32_e32 v82, s29, v82
	s_lshl_b32 s5, s30, 7
	v_add_u32_e32 v0, s5, v156
	v_lshlrev_b32_e32 v0, s28, v0
	v_add_u32_e32 v0, s29, v0
	v_lshl_add_u32 v1, v0, 11, v18
	global_load_dwordx4 v[48:51], v1, s[40:41] nt
	v_add_u32_e32 v0, s5, v157
	v_lshlrev_b32_e32 v0, s28, v0
	v_add_u32_e32 v0, s29, v0
	v_lshl_add_u32 v1, v0, 11, v18
	global_load_dwordx4 v[52:55], v1, s[40:41] nt
	s_cmp_lt_u32 s4, 16
	s_cbranch_scc1 .Latt_odummy_4
	v_lshl_add_u32 v1, v82, 11, v19
	global_load_dwordx4 v[64:67], v1, s[42:43] offset:0
	global_load_dwordx4 v[68:71], v1, s[42:43] offset:64
	v_lshlrev_b32_e32 v0, 2, v82
	global_load_dword v80, v0, s[44:45]
	s_branch .Latt_odone_5

.Latt_odone_5:
	s_mov_b32 s4, 1
	s_lshr_b32 s11, s4, 4
	s_and_b32 s12, s4, 15
	s_lshl_b32 s28, s11, 1
	s_lshl_b32 s13, s64, 4
	s_add_i32 s13, s13, s12
	s_lshr_b32 s14, s12, 2
	s_and_b32 s15, s12, 3
	s_lshl_b32 s16, s64, 2
	s_add_i32 s15, s16, s15
	s_cmp_eq_u32 s11, 1
	s_cselect_b32 s29, s14, 0
	s_cselect_b32 s30, s15, s13
	s_cmp_eq_u32 s11, 2
	s_cselect_b32 s29, s12, s29
	s_cselect_b32 s30, s64, s30
	s_lshl_b32 s5, s30, 7
	v_add_u32_e32 v82, s5, v17
	v_lshlrev_b32_e32 v82, s28, v82
	v_add_u32_e32 v82, s29, v82
	s_lshl_b32 s5, s30, 7
	v_add_u32_e32 v0, s5, v156
	v_lshlrev_b32_e32 v0, s28, v0
	v_add_u32_e32 v0, s29, v0
	v_lshl_add_u32 v1, v0, 11, v18
	global_load_dwordx4 v[56:59], v1, s[40:41] nt
	v_add_u32_e32 v0, s5, v157
	v_lshlrev_b32_e32 v0, s28, v0
	v_add_u32_e32 v0, s29, v0
	v_lshl_add_u32 v1, v0, 11, v18
	global_load_dwordx4 v[60:63], v1, s[40:41] nt
	s_cmp_lt_u32 s4, 16
	s_cbranch_scc1 .Latt_odummy_6
	v_lshl_add_u32 v1, v82, 11, v19
	global_load_dwordx4 v[72:75], v1, s[42:43] offset:0
	global_load_dwordx4 v[76:79], v1, s[42:43] offset:64
	v_lshlrev_b32_e32 v0, 2, v82
	global_load_dword v81, v0, s[44:45]
	s_branch .Latt_odone_7

.Latt_n0t_19:
.Latt_n0skip_11:
	v_mov_b32_dpp v0, v48 quad_perm:[1,0,3,2] row_mask:0xf bank_mask:0xf
	v_mov_b32_dpp v1, v52 quad_perm:[1,0,3,2] row_mask:0xf bank_mask:0xf
	v_cndmask_b32_e64 v48, v48, v1, s[94:95]
	v_cndmask_b32_e64 v52, v0, v52, s[94:95]
	v_mov_b32_dpp v0, v49 quad_perm:[1,0,3,2] row_mask:0xf bank_mask:0xf
	v_mov_b32_dpp v1, v53 quad_perm:[1,0,3,2] row_mask:0xf bank_mask:0xf
	v_cndmask_b32_e64 v49, v49, v1, s[94:95]
	v_cndmask_b32_e64 v53, v0, v53, s[94:95]
	v_mov_b32_dpp v0, v50 quad_perm:[1,0,3,2] row_mask:0xf bank_mask:0xf
	v_mov_b32_dpp v1, v54 quad_perm:[1,0,3,2] row_mask:0xf bank_mask:0xf
	v_cndmask_b32_e64 v50, v50, v1, s[94:95]
	v_cndmask_b32_e64 v54, v0, v54, s[94:95]
	v_mov_b32_dpp v0, v51 quad_perm:[1,0,3,2] row_mask:0xf bank_mask:0xf
	v_mov_b32_dpp v1, v55 quad_perm:[1,0,3,2] row_mask:0xf bank_mask:0xf
	v_cndmask_b32_e64 v51, v51, v1, s[94:95]
	v_cndmask_b32_e64 v55, v0, v55, s[94:95]
	s_nop 1
	s_waitcnt lgkmcnt(10)
	v_mfma_f32_16x16x32_bf16 v[132:135], v[84:87], v[48:51], v[22:25]
	v_mfma_f32_16x16x32_bf16 v[132:135], v[88:91], v[52:55], v[132:135]
	s_waitcnt lgkmcnt(8)
	v_mfma_f32_16x16x32_bf16 v[136:139], v[92:95], v[48:51], v[22:25]
	v_mfma_f32_16x16x32_bf16 v[136:139], v[96:99], v[52:55], v[136:139]
	s_waitcnt lgkmcnt(6)
	v_mfma_f32_16x16x32_bf16 v[140:143], v[100:103], v[48:51], v[22:25]
	v_mfma_f32_16x16x32_bf16 v[140:143], v[104:107], v[52:55], v[140:143]
	s_add_i32 s5, s91, 6
	s_and_b32 s5, s5, 31
	s_lshl_b32 s5, s5, 11
	v_add_u32_e32 v0, s5, v4
	v_add_u32_e32 v1, s5, v5
	ds_read_b128 v[84:87], v0
	ds_read_b128 v[88:91], v1
	s_add_i32 s5, s91, 7
	s_and_b32 s5, s5, 31
	s_lshl_b32 s5, s5, 11
	v_add_u32_e32 v0, s5, v4
	v_add_u32_e32 v1, s5, v5
	ds_read_b128 v[92:95], v0
	ds_read_b128 v[96:99], v1
	s_add_i32 s5, s91, 8
	s_and_b32 s5, s5, 31
	s_lshl_b32 s5, s5, 11
	v_add_u32_e32 v0, s5, v4
	v_add_u32_e32 v1, s5, v5
	ds_read_b128 v[100:103], v0
	ds_read_b128 v[104:107], v1
	s_waitcnt lgkmcnt(10)
	v_mfma_f32_16x16x32_bf16 v[144:147], v[108:111], v[48:51], v[22:25]
	v_mfma_f32_16x16x32_bf16 v[144:147], v[112:115], v[52:55], v[144:147]
	s_waitcnt lgkmcnt(8)
	v_mfma_f32_16x16x32_bf16 v[148:151], v[116:119], v[48:51], v[22:25]
	v_mfma_f32_16x16x32_bf16 v[148:151], v[120:123], v[52:55], v[148:151]
	s_waitcnt lgkmcnt(6)
	v_mfma_f32_16x16x32_bf16 v[152:155], v[124:127], v[48:51], v[22:25]
	v_mfma_f32_16x16x32_bf16 v[152:155], v[128:131], v[52:55], v[152:155]
	s_waitcnt lgkmcnt(4)
	v_mfma_f32_16x16x32_bf16 v[160:163], v[84:87], v[48:51], v[22:25]
	v_mfma_f32_16x16x32_bf16 v[160:163], v[88:91], v[52:55], v[160:163]
	s_waitcnt lgkmcnt(2)
	v_mfma_f32_16x16x32_bf16 v[164:167], v[92:95], v[48:51], v[22:25]
	v_mfma_f32_16x16x32_bf16 v[164:167], v[96:99], v[52:55], v[164:167]
	s_waitcnt lgkmcnt(0)
	v_mfma_f32_16x16x32_bf16 v[168:171], v[100:103], v[48:51], v[22:25]
	v_mfma_f32_16x16x32_bf16 v[168:171], v[104:107], v[52:55], v[168:171]
	s_nop 7
	s_nop 3
	v_cndmask_b32_e64 v132, v132, v223, s[54:55]
	v_cndmask_b32_e64 v133, v133, v223, s[56:57]
	v_cndmask_b32_e64 v134, v134, v223, s[58:59]
	v_cndmask_b32_e64 v135, v135, v223, s[60:61]
	v_cndmask_b32_e64 v168, v168, v223, s[70:71]
	v_cndmask_b32_e64 v169, v169, v223, s[72:73]
	v_cndmask_b32_e64 v170, v170, v223, s[74:75]
	v_cndmask_b32_e64 v171, v171, v223, s[76:77]
	v_max3_f32 v0, v132, v133, v134
	v_max_f32_e32 v0, v0, v135
	v_add_f32_e32 v35, v0, v26
	v_max3_f32 v0, v136, v137, v138
	v_max_f32_e32 v0, v0, v139
	v_add_f32_e32 v0, v0, v27
	v_max_f32_e32 v35, v35, v0
	v_max3_f32 v0, v140, v141, v142
	v_max_f32_e32 v0, v0, v143
	v_add_f32_e32 v0, v0, v28
	v_max_f32_e32 v35, v35, v0
	v_max3_f32 v0, v144, v145, v146
	v_max_f32_e32 v0, v0, v147
	v_add_f32_e32 v0, v0, v29
	v_max_f32_e32 v35, v35, v0
	v_max3_f32 v0, v148, v149, v150
	v_max_f32_e32 v0, v0, v151
	v_add_f32_e32 v0, v0, v30
	v_max_f32_e32 v35, v35, v0
	v_max3_f32 v0, v152, v153, v154
	v_max_f32_e32 v0, v0, v155
	v_add_f32_e32 v0, v0, v31
	v_max_f32_e32 v35, v35, v0
	v_max3_f32 v0, v160, v161, v162
	v_max_f32_e32 v0, v0, v163
	v_add_f32_e32 v0, v0, v32
	v_max_f32_e32 v35, v35, v0
	v_max3_f32 v0, v164, v165, v166
	v_max_f32_e32 v0, v0, v167
	v_add_f32_e32 v0, v0, v33
	v_max_f32_e32 v35, v35, v0
	v_max3_f32 v0, v168, v169, v170
	v_max_f32_e32 v0, v0, v171
	v_add_f32_e32 v0, v0, v34
	v_max_f32_e32 v35, v35, v0
	v_mov_b32_e32 v0, v35
	v_mov_b32_e32 v1, v35
	s_nop 1
	v_permlane16_swap_b32_e32 v0, v1
	s_nop 1
	v_max_f32_e32 v35, v0, v1
	v_mov_b32_e32 v0, v35
	v_mov_b32_e32 v1, v35
	s_nop 1
	v_permlane32_swap_b32_e32 v0, v1
	s_nop 1
	v_max_f32_e32 v35, v0, v1
	v_sub_f32_e32 v2, v26, v35
	v_add_f32_e32 v132, v132, v2
	v_add_f32_e32 v133, v133, v2
	v_add_f32_e32 v134, v134, v2
	v_add_f32_e32 v135, v135, v2
	v_exp_f32_e32 v132, v132
	v_exp_f32_e32 v133, v133
	v_exp_f32_e32 v134, v134
	v_exp_f32_e32 v135, v135
	v_add_f32_e32 v36, 0, v132
	v_add_f32_e32 v36, v133, v36
	v_add_f32_e32 v36, v134, v36
	v_add_f32_e32 v36, v135, v36
	v_cvt_pk_bf16_f32 v172, v132, v133
	v_cvt_pk_bf16_f32 v173, v134, v135
	v_sub_f32_e32 v2, v27, v35
	v_add_f32_e32 v136, v136, v2
	v_add_f32_e32 v137, v137, v2
	v_add_f32_e32 v138, v138, v2
	v_add_f32_e32 v139, v139, v2
	v_exp_f32_e32 v136, v136
	v_exp_f32_e32 v137, v137
	v_exp_f32_e32 v138, v138
	v_exp_f32_e32 v139, v139
	v_add_f32_e32 v36, v136, v36
	v_add_f32_e32 v36, v137, v36
	v_add_f32_e32 v36, v138, v36
	v_add_f32_e32 v36, v139, v36
	v_cvt_pk_bf16_f32 v174, v136, v137
	v_cvt_pk_bf16_f32 v175, v138, v139
	v_sub_f32_e32 v2, v28, v35
	v_add_f32_e32 v140, v140, v2
	v_add_f32_e32 v141, v141, v2
	v_add_f32_e32 v142, v142, v2
	v_add_f32_e32 v143, v143, v2
	v_exp_f32_e32 v140, v140
	v_exp_f32_e32 v141, v141
	v_exp_f32_e32 v142, v142
	v_exp_f32_e32 v143, v143
	v_add_f32_e32 v36, v140, v36
	v_add_f32_e32 v36, v141, v36
	v_add_f32_e32 v36, v142, v36
	v_add_f32_e32 v36, v143, v36
	v_cvt_pk_bf16_f32 v176, v140, v141
	v_cvt_pk_bf16_f32 v177, v142, v143
	v_sub_f32_e32 v2, v29, v35
	v_add_f32_e32 v144, v144, v2
	v_add_f32_e32 v145, v145, v2
	v_add_f32_e32 v146, v146, v2
	v_add_f32_e32 v147, v147, v2
	v_exp_f32_e32 v144, v144
	v_exp_f32_e32 v145, v145
	v_exp_f32_e32 v146, v146
	v_exp_f32_e32 v147, v147
	v_add_f32_e32 v36, v144, v36
	v_add_f32_e32 v36, v145, v36
	v_add_f32_e32 v36, v146, v36
	v_add_f32_e32 v36, v147, v36
	v_cvt_pk_bf16_f32 v178, v144, v145
	v_cvt_pk_bf16_f32 v179, v146, v147
	v_sub_f32_e32 v2, v30, v35
	v_add_f32_e32 v148, v148, v2
	v_add_f32_e32 v149, v149, v2
	v_add_f32_e32 v150, v150, v2
	v_add_f32_e32 v151, v151, v2
	v_exp_f32_e32 v148, v148
	v_exp_f32_e32 v149, v149
	v_exp_f32_e32 v150, v150
	v_exp_f32_e32 v151, v151
	v_add_f32_e32 v36, v148, v36
	v_add_f32_e32 v36, v149, v36
	v_add_f32_e32 v36, v150, v36
	v_add_f32_e32 v36, v151, v36
	v_cvt_pk_bf16_f32 v180, v148, v149
	v_cvt_pk_bf16_f32 v181, v150, v151
	v_sub_f32_e32 v2, v31, v35
	v_add_f32_e32 v152, v152, v2
	v_add_f32_e32 v153, v153, v2
	v_add_f32_e32 v154, v154, v2
	v_add_f32_e32 v155, v155, v2
	v_exp_f32_e32 v152, v152
	v_exp_f32_e32 v153, v153
	v_exp_f32_e32 v154, v154
	v_exp_f32_e32 v155, v155
	v_add_f32_e32 v36, v152, v36
	v_add_f32_e32 v36, v153, v36
	v_add_f32_e32 v36, v154, v36
	v_add_f32_e32 v36, v155, v36
	v_cvt_pk_bf16_f32 v182, v152, v153
	v_cvt_pk_bf16_f32 v183, v154, v155
	v_sub_f32_e32 v2, v32, v35
	v_add_f32_e32 v160, v160, v2
	v_add_f32_e32 v161, v161, v2
	v_add_f32_e32 v162, v162, v2
	v_add_f32_e32 v163, v163, v2
	v_exp_f32_e32 v160, v160
	v_exp_f32_e32 v161, v161
	v_exp_f32_e32 v162, v162
	v_exp_f32_e32 v163, v163
	v_add_f32_e32 v36, v160, v36
	v_add_f32_e32 v36, v161, v36
	v_add_f32_e32 v36, v162, v36
	v_add_f32_e32 v36, v163, v36
	v_cvt_pk_bf16_f32 v184, v160, v161
	v_cvt_pk_bf16_f32 v185, v162, v163
	v_sub_f32_e32 v2, v33, v35
	v_add_f32_e32 v164, v164, v2
	v_add_f32_e32 v165, v165, v2
	v_add_f32_e32 v166, v166, v2
	v_add_f32_e32 v167, v167, v2
	v_exp_f32_e32 v164, v164
	v_exp_f32_e32 v165, v165
	v_exp_f32_e32 v166, v166
	v_exp_f32_e32 v167, v167
	v_add_f32_e32 v36, v164, v36
	v_add_f32_e32 v36, v165, v36
	v_add_f32_e32 v36, v166, v36
	v_add_f32_e32 v36, v167, v36
	v_cvt_pk_bf16_f32 v186, v164, v165
	v_cvt_pk_bf16_f32 v187, v166, v167
	v_sub_f32_e32 v2, v34, v35
	v_add_f32_e32 v168, v168, v2
	v_add_f32_e32 v169, v169, v2
	v_add_f32_e32 v170, v170, v2
	v_add_f32_e32 v171, v171, v2
	v_exp_f32_e32 v168, v168
	v_exp_f32_e32 v169, v169
	v_exp_f32_e32 v170, v170
	v_exp_f32_e32 v171, v171
	v_add_f32_e32 v36, v168, v36
	v_add_f32_e32 v36, v169, v36
	v_add_f32_e32 v36, v170, v36
	v_add_f32_e32 v36, v171, v36
	v_cvt_pk_bf16_f32 v188, v168, v169
	v_cvt_pk_bf16_f32 v189, v170, v171
	v_mov_b32_e32 v2, 0
	s_cmp_eq_u32 s89, 1
	s_cbranch_scc1 .Latt_w14_20
	s_waitcnt vmcnt(12)
	s_branch .Latt_wj_21

.Latt_half_22:
	s_add_i32 s7, s5, 128
	s_and_b32 s7, s7, 511
	s_lshl_b32 s7, s7, 7
	s_add_i32 m0, s7, s49
	s_add_i32 s7, s6, 128
	v_add_u32_e32 v0, s7, v14
	v_lshlrev_b32_e32 v0, s28, v0
	v_add_u32_e32 v0, s29, v0
	v_max_i32_e32 v0, 0, v0
	v_lshl_or_b32 v2, v0, 7, v15
	v_lshl_add_u64 v[42:43], s[50:51], 0, v[2:3]
	global_load_lds_dwordx4 v[42:43], off nt
	s_add_i32 s7, s5, 192
	s_and_b32 s7, s7, 511
	s_lshl_b32 s7, s7, 7
	s_add_i32 m0, s7, s49
	s_add_i32 s7, s6, 192
	v_add_u32_e32 v0, s7, v14
	v_lshlrev_b32_e32 v0, s28, v0
	v_add_u32_e32 v0, s29, v0
	v_max_i32_e32 v0, 0, v0
	v_lshl_or_b32 v2, v0, 7, v15
	v_lshl_add_u64 v[44:45], s[50:51], 0, v[2:3]
	global_load_lds_dwordx4 v[44:45], off nt
	s_add_i32 s4, s53, 2
	s_min_u32 s4, s4, 47
	s_lshr_b32 s11, s4, 4
	s_and_b32 s12, s4, 15
	s_lshl_b32 s8, s11, 1
	s_lshl_b32 s13, s64, 4
	s_add_i32 s13, s13, s12
	s_lshr_b32 s14, s12, 2
	s_and_b32 s15, s12, 3
	s_lshl_b32 s16, s64, 2
	s_add_i32 s15, s16, s15
	s_cmp_eq_u32 s11, 1
	s_cselect_b32 s17, s14, 0
	s_cselect_b32 s10, s15, s13
	s_cmp_eq_u32 s11, 2
	s_cselect_b32 s17, s12, s17
	s_cselect_b32 s10, s64, s10
	s_lshl_b32 s5, s10, 7
	v_add_u32_e32 v82, s5, v17
	v_lshlrev_b32_e32 v82, s8, v82
	v_add_u32_e32 v82, s17, v82
	s_lshl_b32 s5, s10, 7
	v_add_u32_e32 v0, s5, v156
	v_lshlrev_b32_e32 v0, s8, v0
	v_add_u32_e32 v0, s17, v0
	v_lshl_add_u32 v1, v0, 11, v18
	global_load_dwordx4 v[48:51], v1, s[40:41] nt
	v_add_u32_e32 v0, s5, v157
	v_lshlrev_b32_e32 v0, s8, v0
	v_add_u32_e32 v0, s17, v0
	v_lshl_add_u32 v1, v0, 11, v18
	global_load_dwordx4 v[52:55], v1, s[40:41] nt
	s_add_i32 s5, s91, 0
	s_and_b32 s5, s5, 31
	s_lshl_b32 s5, s5, 11
	v_add_u32_e32 v37, s5, v6
	v_add_u32_e32 v38, s5, v7
	v_add_u32_e32 v39, s5, v8
	v_add_u32_e32 v40, s5, v9
	ds_read_b64_tr_b16 v[84:85], v37
	ds_read_b64_tr_b16 v[88:89], v38
	ds_read_b64_tr_b16 v[92:93], v39
	ds_read_b64_tr_b16 v[96:97], v40
	s_add_i32 s5, s91, 1
	s_and_b32 s5, s5, 31
	s_lshl_b32 s5, s5, 11
	v_add_u32_e32 v37, s5, v6
	v_add_u32_e32 v38, s5, v7
	v_add_u32_e32 v39, s5, v8
	v_add_u32_e32 v40, s5, v9
	ds_read_b64_tr_b16 v[86:87], v37
	ds_read_b64_tr_b16 v[90:91], v38
	ds_read_b64_tr_b16 v[94:95], v39
	ds_read_b64_tr_b16 v[98:99], v40
	s_add_i32 s5, s91, 2
	s_and_b32 s5, s5, 31
	s_lshl_b32 s5, s5, 11
	v_add_u32_e32 v37, s5, v6
	v_add_u32_e32 v38, s5, v7
	v_add_u32_e32 v39, s5, v8
	v_add_u32_e32 v40, s5, v9
	ds_read_b64_tr_b16 v[100:101], v37
	ds_read_b64_tr_b16 v[104:105], v38
	ds_read_b64_tr_b16 v[108:109], v39
	ds_read_b64_tr_b16 v[112:113], v40
	s_add_i32 s5, s91, 3
	s_and_b32 s5, s5, 31
	s_lshl_b32 s5, s5, 11
	v_add_u32_e32 v37, s5, v6
	v_add_u32_e32 v38, s5, v7
	v_add_u32_e32 v39, s5, v8
	v_add_u32_e32 v40, s5, v9
	ds_read_b64_tr_b16 v[102:103], v37
	ds_read_b64_tr_b16 v[106:107], v38
	ds_read_b64_tr_b16 v[110:111], v39
	ds_read_b64_tr_b16 v[114:115], v40
	s_waitcnt lgkmcnt(8)
	v_mfma_f32_16x16x32_bf16 v[228:231], v[84:87], v[172:175], 0
	v_mfma_f32_16x16x32_bf16 v[232:235], v[88:91], v[172:175], 0
	v_mfma_f32_16x16x32_bf16 v[236:239], v[92:95], v[172:175], 0
	v_mfma_f32_16x16x32_bf16 v[240:243], v[96:99], v[172:175], 0
	s_add_i32 s5, s91, 4
	s_and_b32 s5, s5, 31
	s_lshl_b32 s5, s5, 11
	v_add_u32_e32 v37, s5, v6
	v_add_u32_e32 v38, s5, v7
	v_add_u32_e32 v39, s5, v8
	v_add_u32_e32 v40, s5, v9
	ds_read_b64_tr_b16 v[84:85], v37
	ds_read_b64_tr_b16 v[88:89], v38
	ds_read_b64_tr_b16 v[92:93], v39
	ds_read_b64_tr_b16 v[96:97], v40
	s_add_i32 s5, s91, 5
	s_and_b32 s5, s5, 31
	s_lshl_b32 s5, s5, 11
	v_add_u32_e32 v37, s5, v6
	v_add_u32_e32 v38, s5, v7
	v_add_u32_e32 v39, s5, v8
	v_add_u32_e32 v40, s5, v9
	ds_read_b64_tr_b16 v[86:87], v37
	ds_read_b64_tr_b16 v[90:91], v38
	ds_read_b64_tr_b16 v[94:95], v39
	ds_read_b64_tr_b16 v[98:99], v40
	s_waitcnt lgkmcnt(8)
	v_mfma_f32_16x16x32_bf16 v[228:231], v[100:103], v[176:179], v[228:231]
	v_mfma_f32_16x16x32_bf16 v[232:235], v[104:107], v[176:179], v[232:235]
	v_mfma_f32_16x16x32_bf16 v[236:239], v[108:111], v[176:179], v[236:239]
	v_mfma_f32_16x16x32_bf16 v[240:243], v[112:115], v[176:179], v[240:243]
	s_add_i32 s5, s91, 6
	s_and_b32 s5, s5, 31
	s_lshl_b32 s5, s5, 11
	v_add_u32_e32 v37, s5, v6
	v_add_u32_e32 v38, s5, v7
	v_add_u32_e32 v39, s5, v8
	v_add_u32_e32 v40, s5, v9
	ds_read_b64_tr_b16 v[100:101], v37
	ds_read_b64_tr_b16 v[104:105], v38
	ds_read_b64_tr_b16 v[108:109], v39
	ds_read_b64_tr_b16 v[112:113], v40
	s_add_i32 s5, s91, 7
	s_and_b32 s5, s5, 31
	s_lshl_b32 s5, s5, 11
	v_add_u32_e32 v37, s5, v6
	v_add_u32_e32 v38, s5, v7
	v_add_u32_e32 v39, s5, v8
	v_add_u32_e32 v40, s5, v9
	ds_read_b64_tr_b16 v[102:103], v37
	ds_read_b64_tr_b16 v[106:107], v38
	ds_read_b64_tr_b16 v[110:111], v39
	ds_read_b64_tr_b16 v[114:115], v40
	s_waitcnt lgkmcnt(8)
	v_mfma_f32_16x16x32_bf16 v[228:231], v[84:87], v[180:183], v[228:231]
	v_mfma_f32_16x16x32_bf16 v[232:235], v[88:91], v[180:183], v[232:235]
	v_mfma_f32_16x16x32_bf16 v[236:239], v[92:95], v[180:183], v[236:239]
	v_mfma_f32_16x16x32_bf16 v[240:243], v[96:99], v[180:183], v[240:243]
	s_add_i32 s5, s91, 8
	s_and_b32 s5, s5, 31
	s_lshl_b32 s5, s5, 11
	v_add_u32_e32 v37, s5, v6
	v_add_u32_e32 v38, s5, v7
	v_add_u32_e32 v39, s5, v8
	v_add_u32_e32 v40, s5, v9
	ds_read_b64_tr_b16 v[84:85], v37
	ds_read_b64_tr_b16 v[88:89], v38
	ds_read_b64_tr_b16 v[92:93], v39
	ds_read_b64_tr_b16 v[96:97], v40
	s_add_i32 s5, s67, 9
	s_min_u32 s5, s5, 15
	s_lshl_b32 s6, s90, 3
	s_add_i32 s5, s5, s6
	s_and_b32 s5, s5, 31
	s_lshl_b32 s5, s5, 11
	v_add_u32_e32 v37, s5, v6
	v_add_u32_e32 v38, s5, v7
	v_add_u32_e32 v39, s5, v8
	v_add_u32_e32 v40, s5, v9
	ds_read_b64_tr_b16 v[86:87], v37
	ds_read_b64_tr_b16 v[90:91], v38
	ds_read_b64_tr_b16 v[94:95], v39
	ds_read_b64_tr_b16 v[98:99], v40
	s_waitcnt lgkmcnt(8)
	v_mfma_f32_16x16x32_bf16 v[228:231], v[100:103], v[184:187], v[228:231]
	v_mfma_f32_16x16x32_bf16 v[232:235], v[104:107], v[184:187], v[232:235]
	v_mfma_f32_16x16x32_bf16 v[236:239], v[108:111], v[184:187], v[236:239]
	v_mfma_f32_16x16x32_bf16 v[240:243], v[112:115], v[184:187], v[240:243]
	s_waitcnt lgkmcnt(0)
	v_mfma_f32_16x16x32_bf16 v[228:231], v[84:87], v[188:191], v[228:231]
	v_mfma_f32_16x16x32_bf16 v[232:235], v[88:91], v[188:191], v[232:235]
	v_mfma_f32_16x16x32_bf16 v[236:239], v[92:95], v[188:191], v[236:239]
	v_mfma_f32_16x16x32_bf16 v[240:243], v[96:99], v[188:191], v[240:243]
	v_mov_b32_e32 v0, v36
	v_mov_b32_e32 v1, v36
	s_nop 1
	v_permlane16_swap_b32_e32 v0, v1
	s_nop 1
	v_add_f32_e32 v36, v0, v1
	v_mov_b32_e32 v0, v36
	v_mov_b32_e32 v1, v36
	s_nop 1
	v_permlane32_swap_b32_e32 v0, v1
	s_nop 1
	v_add_f32_e32 v36, v0, v1
	s_cmp_lt_u32 s53, 16
	s_cbranch_scc0 .Latt_hasprev_23
	v_mov_b32_e32 v80, v223
	v_mov_b32_e32 v64, 0
	v_mov_b32_e32 v65, 0
	v_mov_b32_e32 v66, 0
	v_mov_b32_e32 v67, 0
	v_mov_b32_e32 v68, 0
	v_mov_b32_e32 v69, 0
	v_mov_b32_e32 v70, 0
	v_mov_b32_e32 v71, 0
	s_branch .Latt_noprev_24

.Latt_n0t_38:
.Latt_n0skip_30:
	v_mov_b32_dpp v0, v56 quad_perm:[1,0,3,2] row_mask:0xf bank_mask:0xf
	v_mov_b32_dpp v1, v60 quad_perm:[1,0,3,2] row_mask:0xf bank_mask:0xf
	v_cndmask_b32_e64 v56, v56, v1, s[94:95]
	v_cndmask_b32_e64 v60, v0, v60, s[94:95]
	v_mov_b32_dpp v0, v57 quad_perm:[1,0,3,2] row_mask:0xf bank_mask:0xf
	v_mov_b32_dpp v1, v61 quad_perm:[1,0,3,2] row_mask:0xf bank_mask:0xf
	v_cndmask_b32_e64 v57, v57, v1, s[94:95]
	v_cndmask_b32_e64 v61, v0, v61, s[94:95]
	v_mov_b32_dpp v0, v58 quad_perm:[1,0,3,2] row_mask:0xf bank_mask:0xf
	v_mov_b32_dpp v1, v62 quad_perm:[1,0,3,2] row_mask:0xf bank_mask:0xf
	v_cndmask_b32_e64 v58, v58, v1, s[94:95]
	v_cndmask_b32_e64 v62, v0, v62, s[94:95]
	v_mov_b32_dpp v0, v59 quad_perm:[1,0,3,2] row_mask:0xf bank_mask:0xf
	v_mov_b32_dpp v1, v63 quad_perm:[1,0,3,2] row_mask:0xf bank_mask:0xf
	v_cndmask_b32_e64 v59, v59, v1, s[94:95]
	v_cndmask_b32_e64 v63, v0, v63, s[94:95]
	s_nop 1
	s_waitcnt lgkmcnt(10)
	v_mfma_f32_16x16x32_bf16 v[132:135], v[84:87], v[56:59], v[22:25]
	v_mfma_f32_16x16x32_bf16 v[132:135], v[88:91], v[60:63], v[132:135]
	s_waitcnt lgkmcnt(8)
	v_mfma_f32_16x16x32_bf16 v[136:139], v[92:95], v[56:59], v[22:25]
	v_mfma_f32_16x16x32_bf16 v[136:139], v[96:99], v[60:63], v[136:139]
	s_waitcnt lgkmcnt(6)
	v_mfma_f32_16x16x32_bf16 v[140:143], v[100:103], v[56:59], v[22:25]
	v_mfma_f32_16x16x32_bf16 v[140:143], v[104:107], v[60:63], v[140:143]
	s_add_i32 s5, s91, 6
	s_and_b32 s5, s5, 31
	s_lshl_b32 s5, s5, 11
	v_add_u32_e32 v0, s5, v4
	v_add_u32_e32 v1, s5, v5
	ds_read_b128 v[84:87], v0
	ds_read_b128 v[88:91], v1
	s_add_i32 s5, s91, 7
	s_and_b32 s5, s5, 31
	s_lshl_b32 s5, s5, 11
	v_add_u32_e32 v0, s5, v4
	v_add_u32_e32 v1, s5, v5
	ds_read_b128 v[92:95], v0
	ds_read_b128 v[96:99], v1
	s_add_i32 s5, s91, 8
	s_and_b32 s5, s5, 31
	s_lshl_b32 s5, s5, 11
	v_add_u32_e32 v0, s5, v4
	v_add_u32_e32 v1, s5, v5
	ds_read_b128 v[100:103], v0
	ds_read_b128 v[104:107], v1
	s_waitcnt lgkmcnt(10)
	v_mfma_f32_16x16x32_bf16 v[144:147], v[108:111], v[56:59], v[22:25]
	v_mfma_f32_16x16x32_bf16 v[144:147], v[112:115], v[60:63], v[144:147]
	s_waitcnt lgkmcnt(8)
	v_mfma_f32_16x16x32_bf16 v[148:151], v[116:119], v[56:59], v[22:25]
	v_mfma_f32_16x16x32_bf16 v[148:151], v[120:123], v[60:63], v[148:151]
	s_waitcnt lgkmcnt(6)
	v_mfma_f32_16x16x32_bf16 v[152:155], v[124:127], v[56:59], v[22:25]
	v_mfma_f32_16x16x32_bf16 v[152:155], v[128:131], v[60:63], v[152:155]
	s_waitcnt lgkmcnt(4)
	v_mfma_f32_16x16x32_bf16 v[160:163], v[84:87], v[56:59], v[22:25]
	v_mfma_f32_16x16x32_bf16 v[160:163], v[88:91], v[60:63], v[160:163]
	s_waitcnt lgkmcnt(2)
	v_mfma_f32_16x16x32_bf16 v[164:167], v[92:95], v[56:59], v[22:25]
	v_mfma_f32_16x16x32_bf16 v[164:167], v[96:99], v[60:63], v[164:167]
	s_waitcnt lgkmcnt(0)
	v_mfma_f32_16x16x32_bf16 v[168:171], v[100:103], v[56:59], v[22:25]
	v_mfma_f32_16x16x32_bf16 v[168:171], v[104:107], v[60:63], v[168:171]
	s_nop 7
	s_nop 3
	v_cndmask_b32_e64 v132, v132, v223, s[54:55]
	v_cndmask_b32_e64 v133, v133, v223, s[56:57]
	v_cndmask_b32_e64 v134, v134, v223, s[58:59]
	v_cndmask_b32_e64 v135, v135, v223, s[60:61]
	v_cndmask_b32_e64 v168, v168, v223, s[70:71]
	v_cndmask_b32_e64 v169, v169, v223, s[72:73]
	v_cndmask_b32_e64 v170, v170, v223, s[74:75]
	v_cndmask_b32_e64 v171, v171, v223, s[76:77]
	v_max3_f32 v0, v132, v133, v134
	v_max_f32_e32 v0, v0, v135
	v_add_f32_e32 v35, v0, v26
	v_max3_f32 v0, v136, v137, v138
	v_max_f32_e32 v0, v0, v139
	v_add_f32_e32 v0, v0, v27
	v_max_f32_e32 v35, v35, v0
	v_max3_f32 v0, v140, v141, v142
	v_max_f32_e32 v0, v0, v143
	v_add_f32_e32 v0, v0, v28
	v_max_f32_e32 v35, v35, v0
	v_max3_f32 v0, v144, v145, v146
	v_max_f32_e32 v0, v0, v147
	v_add_f32_e32 v0, v0, v29
	v_max_f32_e32 v35, v35, v0
	v_max3_f32 v0, v148, v149, v150
	v_max_f32_e32 v0, v0, v151
	v_add_f32_e32 v0, v0, v30
	v_max_f32_e32 v35, v35, v0
	v_max3_f32 v0, v152, v153, v154
	v_max_f32_e32 v0, v0, v155
	v_add_f32_e32 v0, v0, v31
	v_max_f32_e32 v35, v35, v0
	v_max3_f32 v0, v160, v161, v162
	v_max_f32_e32 v0, v0, v163
	v_add_f32_e32 v0, v0, v32
	v_max_f32_e32 v35, v35, v0
	v_max3_f32 v0, v164, v165, v166
	v_max_f32_e32 v0, v0, v167
	v_add_f32_e32 v0, v0, v33
	v_max_f32_e32 v35, v35, v0
	v_max3_f32 v0, v168, v169, v170
	v_max_f32_e32 v0, v0, v171
	v_add_f32_e32 v0, v0, v34
	v_max_f32_e32 v35, v35, v0
	v_mov_b32_e32 v0, v35
	v_mov_b32_e32 v1, v35
	s_nop 1
	v_permlane16_swap_b32_e32 v0, v1
	s_nop 1
	v_max_f32_e32 v35, v0, v1
	v_mov_b32_e32 v0, v35
	v_mov_b32_e32 v1, v35
	s_nop 1
	v_permlane32_swap_b32_e32 v0, v1
	s_nop 1
	v_max_f32_e32 v35, v0, v1
	v_sub_f32_e32 v2, v26, v35
	v_add_f32_e32 v132, v132, v2
	v_add_f32_e32 v133, v133, v2
	v_add_f32_e32 v134, v134, v2
	v_add_f32_e32 v135, v135, v2
	v_exp_f32_e32 v132, v132
	v_exp_f32_e32 v133, v133
	v_exp_f32_e32 v134, v134
	v_exp_f32_e32 v135, v135
	v_add_f32_e32 v36, 0, v132
	v_add_f32_e32 v36, v133, v36
	v_add_f32_e32 v36, v134, v36
	v_add_f32_e32 v36, v135, v36
	v_cvt_pk_bf16_f32 v172, v132, v133
	v_cvt_pk_bf16_f32 v173, v134, v135
	v_sub_f32_e32 v2, v27, v35
	v_add_f32_e32 v136, v136, v2
	v_add_f32_e32 v137, v137, v2
	v_add_f32_e32 v138, v138, v2
	v_add_f32_e32 v139, v139, v2
	v_exp_f32_e32 v136, v136
	v_exp_f32_e32 v137, v137
	v_exp_f32_e32 v138, v138
	v_exp_f32_e32 v139, v139
	v_add_f32_e32 v36, v136, v36
	v_add_f32_e32 v36, v137, v36
	v_add_f32_e32 v36, v138, v36
	v_add_f32_e32 v36, v139, v36
	v_cvt_pk_bf16_f32 v174, v136, v137
	v_cvt_pk_bf16_f32 v175, v138, v139
	v_sub_f32_e32 v2, v28, v35
	v_add_f32_e32 v140, v140, v2
	v_add_f32_e32 v141, v141, v2
	v_add_f32_e32 v142, v142, v2
	v_add_f32_e32 v143, v143, v2
	v_exp_f32_e32 v140, v140
	v_exp_f32_e32 v141, v141
	v_exp_f32_e32 v142, v142
	v_exp_f32_e32 v143, v143
	v_add_f32_e32 v36, v140, v36
	v_add_f32_e32 v36, v141, v36
	v_add_f32_e32 v36, v142, v36
	v_add_f32_e32 v36, v143, v36
	v_cvt_pk_bf16_f32 v176, v140, v141
	v_cvt_pk_bf16_f32 v177, v142, v143
	v_sub_f32_e32 v2, v29, v35
	v_add_f32_e32 v144, v144, v2
	v_add_f32_e32 v145, v145, v2
	v_add_f32_e32 v146, v146, v2
	v_add_f32_e32 v147, v147, v2
	v_exp_f32_e32 v144, v144
	v_exp_f32_e32 v145, v145
	v_exp_f32_e32 v146, v146
	v_exp_f32_e32 v147, v147
	v_add_f32_e32 v36, v144, v36
	v_add_f32_e32 v36, v145, v36
	v_add_f32_e32 v36, v146, v36
	v_add_f32_e32 v36, v147, v36
	v_cvt_pk_bf16_f32 v178, v144, v145
	v_cvt_pk_bf16_f32 v179, v146, v147
	v_sub_f32_e32 v2, v30, v35
	v_add_f32_e32 v148, v148, v2
	v_add_f32_e32 v149, v149, v2
	v_add_f32_e32 v150, v150, v2
	v_add_f32_e32 v151, v151, v2
	v_exp_f32_e32 v148, v148
	v_exp_f32_e32 v149, v149
	v_exp_f32_e32 v150, v150
	v_exp_f32_e32 v151, v151
	v_add_f32_e32 v36, v148, v36
	v_add_f32_e32 v36, v149, v36
	v_add_f32_e32 v36, v150, v36
	v_add_f32_e32 v36, v151, v36
	v_cvt_pk_bf16_f32 v180, v148, v149
	v_cvt_pk_bf16_f32 v181, v150, v151
	v_sub_f32_e32 v2, v31, v35
	v_add_f32_e32 v152, v152, v2
	v_add_f32_e32 v153, v153, v2
	v_add_f32_e32 v154, v154, v2
	v_add_f32_e32 v155, v155, v2
	v_exp_f32_e32 v152, v152
	v_exp_f32_e32 v153, v153
	v_exp_f32_e32 v154, v154
	v_exp_f32_e32 v155, v155
	v_add_f32_e32 v36, v152, v36
	v_add_f32_e32 v36, v153, v36
	v_add_f32_e32 v36, v154, v36
	v_add_f32_e32 v36, v155, v36
	v_cvt_pk_bf16_f32 v182, v152, v153
	v_cvt_pk_bf16_f32 v183, v154, v155
	v_sub_f32_e32 v2, v32, v35
	v_add_f32_e32 v160, v160, v2
	v_add_f32_e32 v161, v161, v2
	v_add_f32_e32 v162, v162, v2
	v_add_f32_e32 v163, v163, v2
	v_exp_f32_e32 v160, v160
	v_exp_f32_e32 v161, v161
	v_exp_f32_e32 v162, v162
	v_exp_f32_e32 v163, v163
	v_add_f32_e32 v36, v160, v36
	v_add_f32_e32 v36, v161, v36
	v_add_f32_e32 v36, v162, v36
	v_add_f32_e32 v36, v163, v36
	v_cvt_pk_bf16_f32 v184, v160, v161
	v_cvt_pk_bf16_f32 v185, v162, v163
	v_sub_f32_e32 v2, v33, v35
	v_add_f32_e32 v164, v164, v2
	v_add_f32_e32 v165, v165, v2
	v_add_f32_e32 v166, v166, v2
	v_add_f32_e32 v167, v167, v2
	v_exp_f32_e32 v164, v164
	v_exp_f32_e32 v165, v165
	v_exp_f32_e32 v166, v166
	v_exp_f32_e32 v167, v167
	v_add_f32_e32 v36, v164, v36
	v_add_f32_e32 v36, v165, v36
	v_add_f32_e32 v36, v166, v36
	v_add_f32_e32 v36, v167, v36
	v_cvt_pk_bf16_f32 v186, v164, v165
	v_cvt_pk_bf16_f32 v187, v166, v167
	v_sub_f32_e32 v2, v34, v35
	v_add_f32_e32 v168, v168, v2
	v_add_f32_e32 v169, v169, v2
	v_add_f32_e32 v170, v170, v2
	v_add_f32_e32 v171, v171, v2
	v_exp_f32_e32 v168, v168
	v_exp_f32_e32 v169, v169
	v_exp_f32_e32 v170, v170
	v_exp_f32_e32 v171, v171
	v_add_f32_e32 v36, v168, v36
	v_add_f32_e32 v36, v169, v36
	v_add_f32_e32 v36, v170, v36
	v_add_f32_e32 v36, v171, v36
	v_cvt_pk_bf16_f32 v188, v168, v169
	v_cvt_pk_bf16_f32 v189, v170, v171
	v_mov_b32_e32 v2, 0
	s_cmp_eq_u32 s89, 1
	s_cbranch_scc1 .Latt_w14_39
	s_waitcnt vmcnt(12)
	s_branch .Latt_wj_40

.Latt_half_41:
	s_add_i32 s7, s5, 128
	s_and_b32 s7, s7, 511
	s_lshl_b32 s7, s7, 7
	s_add_i32 m0, s7, s49
	s_add_i32 s7, s6, 128
	v_add_u32_e32 v0, s7, v14
	v_lshlrev_b32_e32 v0, s28, v0
	v_add_u32_e32 v0, s29, v0
	v_max_i32_e32 v0, 0, v0
	v_lshl_or_b32 v2, v0, 7, v15
	v_lshl_add_u64 v[42:43], s[50:51], 0, v[2:3]
	global_load_lds_dwordx4 v[42:43], off nt
	s_add_i32 s7, s5, 192
	s_and_b32 s7, s7, 511
	s_lshl_b32 s7, s7, 7
	s_add_i32 m0, s7, s49
	s_add_i32 s7, s6, 192
	v_add_u32_e32 v0, s7, v14
	v_lshlrev_b32_e32 v0, s28, v0
	v_add_u32_e32 v0, s29, v0
	v_max_i32_e32 v0, 0, v0
	v_lshl_or_b32 v2, v0, 7, v15
	v_lshl_add_u64 v[44:45], s[50:51], 0, v[2:3]
	global_load_lds_dwordx4 v[44:45], off nt
	s_add_i32 s4, s9, 2
	s_min_u32 s4, s4, 47
	s_lshr_b32 s11, s4, 4
	s_and_b32 s12, s4, 15
	s_lshl_b32 s8, s11, 1
	s_lshl_b32 s13, s64, 4
	s_add_i32 s13, s13, s12
	s_lshr_b32 s14, s12, 2
	s_and_b32 s15, s12, 3
	s_lshl_b32 s16, s64, 2
	s_add_i32 s15, s16, s15
	s_cmp_eq_u32 s11, 1
	s_cselect_b32 s17, s14, 0
	s_cselect_b32 s10, s15, s13
	s_cmp_eq_u32 s11, 2
	s_cselect_b32 s17, s12, s17
	s_cselect_b32 s10, s64, s10
	s_lshl_b32 s5, s10, 7
	v_add_u32_e32 v82, s5, v17
	v_lshlrev_b32_e32 v82, s8, v82
	v_add_u32_e32 v82, s17, v82
	s_lshl_b32 s5, s10, 7
	v_add_u32_e32 v0, s5, v156
	v_lshlrev_b32_e32 v0, s8, v0
	v_add_u32_e32 v0, s17, v0
	v_lshl_add_u32 v1, v0, 11, v18
	global_load_dwordx4 v[56:59], v1, s[40:41] nt
	v_add_u32_e32 v0, s5, v157
	v_lshlrev_b32_e32 v0, s8, v0
	v_add_u32_e32 v0, s17, v0
	v_lshl_add_u32 v1, v0, 11, v18
	global_load_dwordx4 v[60:63], v1, s[40:41] nt
	s_add_i32 s5, s91, 0
	s_and_b32 s5, s5, 31
	s_lshl_b32 s5, s5, 11
	v_add_u32_e32 v37, s5, v6
	v_add_u32_e32 v38, s5, v7
	v_add_u32_e32 v39, s5, v8
	v_add_u32_e32 v40, s5, v9
	ds_read_b64_tr_b16 v[84:85], v37
	ds_read_b64_tr_b16 v[88:89], v38
	ds_read_b64_tr_b16 v[92:93], v39
	ds_read_b64_tr_b16 v[96:97], v40
	s_add_i32 s5, s91, 1
	s_and_b32 s5, s5, 31
	s_lshl_b32 s5, s5, 11
	v_add_u32_e32 v37, s5, v6
	v_add_u32_e32 v38, s5, v7
	v_add_u32_e32 v39, s5, v8
	v_add_u32_e32 v40, s5, v9
	ds_read_b64_tr_b16 v[86:87], v37
	ds_read_b64_tr_b16 v[90:91], v38
	ds_read_b64_tr_b16 v[94:95], v39
	ds_read_b64_tr_b16 v[98:99], v40
	s_add_i32 s5, s91, 2
	s_and_b32 s5, s5, 31
	s_lshl_b32 s5, s5, 11
	v_add_u32_e32 v37, s5, v6
	v_add_u32_e32 v38, s5, v7
	v_add_u32_e32 v39, s5, v8
	v_add_u32_e32 v40, s5, v9
	ds_read_b64_tr_b16 v[100:101], v37
	ds_read_b64_tr_b16 v[104:105], v38
	ds_read_b64_tr_b16 v[108:109], v39
	ds_read_b64_tr_b16 v[112:113], v40
	s_add_i32 s5, s91, 3
	s_and_b32 s5, s5, 31
	s_lshl_b32 s5, s5, 11
	v_add_u32_e32 v37, s5, v6
	v_add_u32_e32 v38, s5, v7
	v_add_u32_e32 v39, s5, v8
	v_add_u32_e32 v40, s5, v9
	ds_read_b64_tr_b16 v[102:103], v37
	ds_read_b64_tr_b16 v[106:107], v38
	ds_read_b64_tr_b16 v[110:111], v39
	ds_read_b64_tr_b16 v[114:115], v40
	s_waitcnt lgkmcnt(8)
	v_mfma_f32_16x16x32_bf16 v[228:231], v[84:87], v[172:175], 0
	v_mfma_f32_16x16x32_bf16 v[232:235], v[88:91], v[172:175], 0
	v_mfma_f32_16x16x32_bf16 v[236:239], v[92:95], v[172:175], 0
	v_mfma_f32_16x16x32_bf16 v[240:243], v[96:99], v[172:175], 0
	s_add_i32 s5, s91, 4
	s_and_b32 s5, s5, 31
	s_lshl_b32 s5, s5, 11
	v_add_u32_e32 v37, s5, v6
	v_add_u32_e32 v38, s5, v7
	v_add_u32_e32 v39, s5, v8
	v_add_u32_e32 v40, s5, v9
	ds_read_b64_tr_b16 v[84:85], v37
	ds_read_b64_tr_b16 v[88:89], v38
	ds_read_b64_tr_b16 v[92:93], v39
	ds_read_b64_tr_b16 v[96:97], v40
	s_add_i32 s5, s91, 5
	s_and_b32 s5, s5, 31
	s_lshl_b32 s5, s5, 11
	v_add_u32_e32 v37, s5, v6
	v_add_u32_e32 v38, s5, v7
	v_add_u32_e32 v39, s5, v8
	v_add_u32_e32 v40, s5, v9
	ds_read_b64_tr_b16 v[86:87], v37
	ds_read_b64_tr_b16 v[90:91], v38
	ds_read_b64_tr_b16 v[94:95], v39
	ds_read_b64_tr_b16 v[98:99], v40
	s_waitcnt lgkmcnt(8)
	v_mfma_f32_16x16x32_bf16 v[228:231], v[100:103], v[176:179], v[228:231]
	v_mfma_f32_16x16x32_bf16 v[232:235], v[104:107], v[176:179], v[232:235]
	v_mfma_f32_16x16x32_bf16 v[236:239], v[108:111], v[176:179], v[236:239]
	v_mfma_f32_16x16x32_bf16 v[240:243], v[112:115], v[176:179], v[240:243]
	s_add_i32 s5, s91, 6
	s_and_b32 s5, s5, 31
	s_lshl_b32 s5, s5, 11
	v_add_u32_e32 v37, s5, v6
	v_add_u32_e32 v38, s5, v7
	v_add_u32_e32 v39, s5, v8
	v_add_u32_e32 v40, s5, v9
	ds_read_b64_tr_b16 v[100:101], v37
	ds_read_b64_tr_b16 v[104:105], v38
	ds_read_b64_tr_b16 v[108:109], v39
	ds_read_b64_tr_b16 v[112:113], v40
	s_add_i32 s5, s91, 7
	s_and_b32 s5, s5, 31
	s_lshl_b32 s5, s5, 11
	v_add_u32_e32 v37, s5, v6
	v_add_u32_e32 v38, s5, v7
	v_add_u32_e32 v39, s5, v8
	v_add_u32_e32 v40, s5, v9
	ds_read_b64_tr_b16 v[102:103], v37
	ds_read_b64_tr_b16 v[106:107], v38
	ds_read_b64_tr_b16 v[110:111], v39
	ds_read_b64_tr_b16 v[114:115], v40
	s_waitcnt lgkmcnt(8)
	v_mfma_f32_16x16x32_bf16 v[228:231], v[84:87], v[180:183], v[228:231]
	v_mfma_f32_16x16x32_bf16 v[232:235], v[88:91], v[180:183], v[232:235]
	v_mfma_f32_16x16x32_bf16 v[236:239], v[92:95], v[180:183], v[236:239]
	v_mfma_f32_16x16x32_bf16 v[240:243], v[96:99], v[180:183], v[240:243]
	s_add_i32 s5, s91, 8
	s_and_b32 s5, s5, 31
	s_lshl_b32 s5, s5, 11
	v_add_u32_e32 v37, s5, v6
	v_add_u32_e32 v38, s5, v7
	v_add_u32_e32 v39, s5, v8
	v_add_u32_e32 v40, s5, v9
	ds_read_b64_tr_b16 v[84:85], v37
	ds_read_b64_tr_b16 v[88:89], v38
	ds_read_b64_tr_b16 v[92:93], v39
	ds_read_b64_tr_b16 v[96:97], v40
	s_add_i32 s5, s67, 9
	s_min_u32 s5, s5, 15
	s_lshl_b32 s6, s90, 3
	s_add_i32 s5, s5, s6
	s_and_b32 s5, s5, 31
	s_lshl_b32 s5, s5, 11
	v_add_u32_e32 v37, s5, v6
	v_add_u32_e32 v38, s5, v7
	v_add_u32_e32 v39, s5, v8
	v_add_u32_e32 v40, s5, v9
	ds_read_b64_tr_b16 v[86:87], v37
	ds_read_b64_tr_b16 v[90:91], v38
	ds_read_b64_tr_b16 v[94:95], v39
	ds_read_b64_tr_b16 v[98:99], v40
	s_waitcnt lgkmcnt(8)
	v_mfma_f32_16x16x32_bf16 v[228:231], v[100:103], v[184:187], v[228:231]
	v_mfma_f32_16x16x32_bf16 v[232:235], v[104:107], v[184:187], v[232:235]
	v_mfma_f32_16x16x32_bf16 v[236:239], v[108:111], v[184:187], v[236:239]
	v_mfma_f32_16x16x32_bf16 v[240:243], v[112:115], v[184:187], v[240:243]
	s_waitcnt lgkmcnt(0)
	v_mfma_f32_16x16x32_bf16 v[228:231], v[84:87], v[188:191], v[228:231]
	v_mfma_f32_16x16x32_bf16 v[232:235], v[88:91], v[188:191], v[232:235]
	v_mfma_f32_16x16x32_bf16 v[236:239], v[92:95], v[188:191], v[236:239]
	v_mfma_f32_16x16x32_bf16 v[240:243], v[96:99], v[188:191], v[240:243]
	v_mov_b32_e32 v0, v36
	v_mov_b32_e32 v1, v36
	s_nop 1
	v_permlane16_swap_b32_e32 v0, v1
	s_nop 1
	v_add_f32_e32 v36, v0, v1
	v_mov_b32_e32 v0, v36
	v_mov_b32_e32 v1, v36
	s_nop 1
	v_permlane32_swap_b32_e32 v0, v1
	s_nop 1
	v_add_f32_e32 v36, v0, v1
	s_cmp_lt_u32 s9, 16
	s_cbranch_scc0 .Latt_hasprev_42
	v_mov_b32_e32 v81, v223
	v_mov_b32_e32 v72, 0
	v_mov_b32_e32 v73, 0
	v_mov_b32_e32 v74, 0
	v_mov_b32_e32 v75, 0
	v_mov_b32_e32 v76, 0
	v_mov_b32_e32 v77, 0
	v_mov_b32_e32 v78, 0
	v_mov_b32_e32 v79, 0
	s_branch .Latt_noprev_43
